# accumulator zeroing removed: first K-tile MFMAs of each unit use SrcC=0 (flag-selected copy of the MFMA blocks)
# speedup vs baseline: 1.0051x; 1.0040x over previous
.LBB0_189:
	s_add_u32 s66, s66, 0x100
	s_addc_u32 s67, s67, 0
	s_add_u32 s64, s64, 0x40080
	v_mov_b32_e32 v2, 0
	s_addc_u32 s65, s65, 0
	s_mov_b32 s68, -2
	s_mov_b32 s99, 1

.Lsk1_p1:
	s_waitcnt lgkmcnt(0)
	s_barrier
	s_setprio 1
	s_cmp_lg_u32 s99, 0
	s_cbranch_scc1 .Lz1_p1
	v_mfma_f32_16x16x32_bf16 v[126:129], v[130:133], v[162:165], v[126:129]
	v_mfma_f32_16x16x32_bf16 v[122:125], v[148:151], v[162:165], v[122:125]
	v_mfma_f32_16x16x32_bf16 v[118:121], v[130:133], v[170:173], v[118:121]
	v_mfma_f32_16x16x32_bf16 v[114:117], v[148:151], v[170:173], v[114:117]
	v_mfma_f32_16x16x32_bf16 v[110:113], v[130:133], v[178:181], v[110:113]
	v_mfma_f32_16x16x32_bf16 v[106:109], v[148:151], v[178:181], v[106:109]
	v_mfma_f32_16x16x32_bf16 v[102:105], v[130:133], v[186:189], v[102:105]
	v_mfma_f32_16x16x32_bf16 v[98:101], v[148:151], v[186:189], v[98:101]
	v_mfma_f32_16x16x32_bf16 v[126:129], v[134:137], v[166:169], v[126:129]
	v_mfma_f32_16x16x32_bf16 v[122:125], v[158:161], v[166:169], v[122:125]
	v_mfma_f32_16x16x32_bf16 v[118:121], v[134:137], v[174:177], v[118:121]
	v_mfma_f32_16x16x32_bf16 v[114:117], v[158:161], v[174:177], v[114:117]
	v_mfma_f32_16x16x32_bf16 v[110:113], v[134:137], v[182:185], v[110:113]
	v_mfma_f32_16x16x32_bf16 v[106:109], v[158:161], v[182:185], v[106:109]
	v_mfma_f32_16x16x32_bf16 v[102:105], v[134:137], v[190:193], v[102:105]
	v_mfma_f32_16x16x32_bf16 v[98:101], v[158:161], v[190:193], v[98:101]
	v_mfma_f32_16x16x32_bf16 v[62:65], v[194:197], v[162:165], v[62:65]
	v_mfma_f32_16x16x32_bf16 v[58:61], v[202:205], v[162:165], v[58:61]
	v_mfma_f32_16x16x32_bf16 v[54:57], v[194:197], v[170:173], v[54:57]
	v_mfma_f32_16x16x32_bf16 v[50:53], v[202:205], v[170:173], v[50:53]
	v_mfma_f32_16x16x32_bf16 v[46:49], v[194:197], v[178:181], v[46:49]
	v_mfma_f32_16x16x32_bf16 v[42:45], v[202:205], v[178:181], v[42:45]
	v_mfma_f32_16x16x32_bf16 v[38:41], v[194:197], v[186:189], v[38:41]
	v_mfma_f32_16x16x32_bf16 v[34:37], v[202:205], v[186:189], v[34:37]
	v_mfma_f32_16x16x32_bf16 v[62:65], v[198:201], v[166:169], v[62:65]
	v_mfma_f32_16x16x32_bf16 v[58:61], v[206:209], v[166:169], v[58:61]
	v_mfma_f32_16x16x32_bf16 v[54:57], v[198:201], v[174:177], v[54:57]
	v_mfma_f32_16x16x32_bf16 v[50:53], v[206:209], v[174:177], v[50:53]
	v_mfma_f32_16x16x32_bf16 v[46:49], v[198:201], v[182:185], v[46:49]
	v_mfma_f32_16x16x32_bf16 v[42:45], v[206:209], v[182:185], v[42:45]
	v_mfma_f32_16x16x32_bf16 v[38:41], v[198:201], v[190:193], v[38:41]
	v_mfma_f32_16x16x32_bf16 v[34:37], v[206:209], v[190:193], v[34:37]
	s_branch .Lz1e_p1
.Lz1_p1:
	v_mfma_f32_16x16x32_bf16 v[126:129], v[130:133], v[162:165], 0
	v_mfma_f32_16x16x32_bf16 v[122:125], v[148:151], v[162:165], 0
	v_mfma_f32_16x16x32_bf16 v[118:121], v[130:133], v[170:173], 0
	v_mfma_f32_16x16x32_bf16 v[114:117], v[148:151], v[170:173], 0
	v_mfma_f32_16x16x32_bf16 v[110:113], v[130:133], v[178:181], 0
	v_mfma_f32_16x16x32_bf16 v[106:109], v[148:151], v[178:181], 0
	v_mfma_f32_16x16x32_bf16 v[102:105], v[130:133], v[186:189], 0
	v_mfma_f32_16x16x32_bf16 v[98:101], v[148:151], v[186:189], 0
	v_mfma_f32_16x16x32_bf16 v[126:129], v[134:137], v[166:169], v[126:129]
	v_mfma_f32_16x16x32_bf16 v[122:125], v[158:161], v[166:169], v[122:125]
	v_mfma_f32_16x16x32_bf16 v[118:121], v[134:137], v[174:177], v[118:121]
	v_mfma_f32_16x16x32_bf16 v[114:117], v[158:161], v[174:177], v[114:117]
	v_mfma_f32_16x16x32_bf16 v[110:113], v[134:137], v[182:185], v[110:113]
	v_mfma_f32_16x16x32_bf16 v[106:109], v[158:161], v[182:185], v[106:109]
	v_mfma_f32_16x16x32_bf16 v[102:105], v[134:137], v[190:193], v[102:105]
	v_mfma_f32_16x16x32_bf16 v[98:101], v[158:161], v[190:193], v[98:101]
	v_mfma_f32_16x16x32_bf16 v[62:65], v[194:197], v[162:165], 0
	v_mfma_f32_16x16x32_bf16 v[58:61], v[202:205], v[162:165], 0
	v_mfma_f32_16x16x32_bf16 v[54:57], v[194:197], v[170:173], 0
	v_mfma_f32_16x16x32_bf16 v[50:53], v[202:205], v[170:173], 0
	v_mfma_f32_16x16x32_bf16 v[46:49], v[194:197], v[178:181], 0
	v_mfma_f32_16x16x32_bf16 v[42:45], v[202:205], v[178:181], 0
	v_mfma_f32_16x16x32_bf16 v[38:41], v[194:197], v[186:189], 0
	v_mfma_f32_16x16x32_bf16 v[34:37], v[202:205], v[186:189], 0
	v_mfma_f32_16x16x32_bf16 v[62:65], v[198:201], v[166:169], v[62:65]
	v_mfma_f32_16x16x32_bf16 v[58:61], v[206:209], v[166:169], v[58:61]
	v_mfma_f32_16x16x32_bf16 v[54:57], v[198:201], v[174:177], v[54:57]
	v_mfma_f32_16x16x32_bf16 v[50:53], v[206:209], v[174:177], v[50:53]
	v_mfma_f32_16x16x32_bf16 v[46:49], v[198:201], v[182:185], v[46:49]
	v_mfma_f32_16x16x32_bf16 v[42:45], v[206:209], v[182:185], v[42:45]
	v_mfma_f32_16x16x32_bf16 v[38:41], v[198:201], v[190:193], v[38:41]
	v_mfma_f32_16x16x32_bf16 v[34:37], v[206:209], v[190:193], v[34:37]
.Lz1e_p1:
	s_setprio 0
	s_barrier
	ds_read_b128 v[162:165], v156 offset:16384
	ds_read_b128 v[166:169], v156 offset:17408
	ds_read_b128 v[170:173], v156 offset:18432
	ds_read_b128 v[174:177], v156 offset:19456
	ds_read_b128 v[178:181], v156 offset:20480
	ds_read_b128 v[182:185], v156 offset:21504
	ds_read_b128 v[186:189], v156 offset:22528
	ds_read_b128 v[190:193], v156 offset:23552
	v_lshl_add_u64 v[212:213], s[0:1], 0, v[140:141]
	v_lshl_add_u64 v[210:211], s[30:31], 0, v[138:139]
	s_add_i32 s30, s75, s5
	s_mov_b32 m0, s30
	s_nop 0
	global_load_lds_dwordx4 v[210:211], off
	v_lshl_add_u64 v[214:215], v[210:211], 0, s[14:15]
	s_add_i32 m0, s30, 0x2000
	s_nop 0
	global_load_lds_dwordx4 v[214:215], off
	s_add_i32 s0, s76, s5
	v_lshl_add_u64 v[250:251], v[210:211], 0, s[16:17]
	s_mov_b32 m0, s0
	s_nop 0
	global_load_lds_dwordx4 v[250:251], off
	v_lshl_add_u64 v[250:251], v[210:211], 0, s[18:19]
	s_add_i32 m0, s0, 0x2000
	s_nop 0
	global_load_lds_dwordx4 v[250:251], off
	s_mov_b32 m0, s7
	s_nop 0
	global_load_lds_dwordx4 v[212:213], off
	v_lshl_add_u64 v[214:215], v[212:213], 0, s[14:15]
	s_mov_b32 m0, s24
	s_nop 0
	global_load_lds_dwordx4 v[214:215], off
	s_cmp_lg_u32 s98, 0
	s_cbranch_scc1 .Lsk2_p1
	s_waitcnt vmcnt(8)
	s_branch .Lsk3_p1

.Lsk3_p1:
	s_waitcnt lgkmcnt(0)
	s_barrier
	s_setprio 1
	s_cmp_lg_u32 s99, 0
	s_cbranch_scc1 .Lz2_p1
	v_mfma_f32_16x16x32_bf16 v[94:97], v[130:133], v[162:165], v[94:97]
	v_mfma_f32_16x16x32_bf16 v[90:93], v[148:151], v[162:165], v[90:93]
	v_mfma_f32_16x16x32_bf16 v[86:89], v[130:133], v[170:173], v[86:89]
	v_mfma_f32_16x16x32_bf16 v[82:85], v[148:151], v[170:173], v[82:85]
	v_mfma_f32_16x16x32_bf16 v[78:81], v[130:133], v[178:181], v[78:81]
	v_mfma_f32_16x16x32_bf16 v[74:77], v[148:151], v[178:181], v[74:77]
	v_mfma_f32_16x16x32_bf16 v[70:73], v[130:133], v[186:189], v[70:73]
	v_mfma_f32_16x16x32_bf16 v[66:69], v[148:151], v[186:189], v[66:69]
	v_mfma_f32_16x16x32_bf16 v[94:97], v[134:137], v[166:169], v[94:97]
	v_mfma_f32_16x16x32_bf16 v[90:93], v[158:161], v[166:169], v[90:93]
	v_mfma_f32_16x16x32_bf16 v[86:89], v[134:137], v[174:177], v[86:89]
	v_mfma_f32_16x16x32_bf16 v[82:85], v[158:161], v[174:177], v[82:85]
	v_mfma_f32_16x16x32_bf16 v[78:81], v[134:137], v[182:185], v[78:81]
	v_mfma_f32_16x16x32_bf16 v[74:77], v[158:161], v[182:185], v[74:77]
	v_mfma_f32_16x16x32_bf16 v[70:73], v[134:137], v[190:193], v[70:73]
	v_mfma_f32_16x16x32_bf16 v[66:69], v[158:161], v[190:193], v[66:69]
	v_mfma_f32_16x16x32_bf16 v[30:33], v[194:197], v[162:165], v[30:33]
	v_mfma_f32_16x16x32_bf16 v[26:29], v[202:205], v[162:165], v[26:29]
	v_mfma_f32_16x16x32_bf16 v[22:25], v[194:197], v[170:173], v[22:25]
	v_mfma_f32_16x16x32_bf16 v[18:21], v[202:205], v[170:173], v[18:21]
	v_mfma_f32_16x16x32_bf16 v[14:17], v[194:197], v[178:181], v[14:17]
	v_mfma_f32_16x16x32_bf16 v[10:13], v[202:205], v[178:181], v[10:13]
	v_mfma_f32_16x16x32_bf16 v[6:9], v[194:197], v[186:189], v[6:9]
	v_mfma_f32_16x16x32_bf16 v[2:5], v[202:205], v[186:189], v[2:5]
	v_mfma_f32_16x16x32_bf16 v[30:33], v[198:201], v[166:169], v[30:33]
	v_mfma_f32_16x16x32_bf16 v[26:29], v[206:209], v[166:169], v[26:29]
	v_mfma_f32_16x16x32_bf16 v[22:25], v[198:201], v[174:177], v[22:25]
	v_mfma_f32_16x16x32_bf16 v[18:21], v[206:209], v[174:177], v[18:21]
	v_mfma_f32_16x16x32_bf16 v[14:17], v[198:201], v[182:185], v[14:17]
	v_mfma_f32_16x16x32_bf16 v[10:13], v[206:209], v[182:185], v[10:13]
	v_mfma_f32_16x16x32_bf16 v[6:9], v[198:201], v[190:193], v[6:9]
	v_mfma_f32_16x16x32_bf16 v[2:5], v[206:209], v[190:193], v[2:5]
	s_branch .Lz2e_p1
.Lz2_p1:
	v_mfma_f32_16x16x32_bf16 v[94:97], v[130:133], v[162:165], 0
	v_mfma_f32_16x16x32_bf16 v[90:93], v[148:151], v[162:165], 0
	v_mfma_f32_16x16x32_bf16 v[86:89], v[130:133], v[170:173], 0
	v_mfma_f32_16x16x32_bf16 v[82:85], v[148:151], v[170:173], 0
	v_mfma_f32_16x16x32_bf16 v[78:81], v[130:133], v[178:181], 0
	v_mfma_f32_16x16x32_bf16 v[74:77], v[148:151], v[178:181], 0
	v_mfma_f32_16x16x32_bf16 v[70:73], v[130:133], v[186:189], 0
	v_mfma_f32_16x16x32_bf16 v[66:69], v[148:151], v[186:189], 0
	v_mfma_f32_16x16x32_bf16 v[94:97], v[134:137], v[166:169], v[94:97]
	v_mfma_f32_16x16x32_bf16 v[90:93], v[158:161], v[166:169], v[90:93]
	v_mfma_f32_16x16x32_bf16 v[86:89], v[134:137], v[174:177], v[86:89]
	v_mfma_f32_16x16x32_bf16 v[82:85], v[158:161], v[174:177], v[82:85]
	v_mfma_f32_16x16x32_bf16 v[78:81], v[134:137], v[182:185], v[78:81]
	v_mfma_f32_16x16x32_bf16 v[74:77], v[158:161], v[182:185], v[74:77]
	v_mfma_f32_16x16x32_bf16 v[70:73], v[134:137], v[190:193], v[70:73]
	v_mfma_f32_16x16x32_bf16 v[66:69], v[158:161], v[190:193], v[66:69]
	v_mfma_f32_16x16x32_bf16 v[30:33], v[194:197], v[162:165], 0
	v_mfma_f32_16x16x32_bf16 v[26:29], v[202:205], v[162:165], 0
	v_mfma_f32_16x16x32_bf16 v[22:25], v[194:197], v[170:173], 0
	v_mfma_f32_16x16x32_bf16 v[18:21], v[202:205], v[170:173], 0
	v_mfma_f32_16x16x32_bf16 v[14:17], v[194:197], v[178:181], 0
	v_mfma_f32_16x16x32_bf16 v[10:13], v[202:205], v[178:181], 0
	v_mfma_f32_16x16x32_bf16 v[6:9], v[194:197], v[186:189], 0
	v_mfma_f32_16x16x32_bf16 v[2:5], v[202:205], v[186:189], 0
	v_mfma_f32_16x16x32_bf16 v[30:33], v[198:201], v[166:169], v[30:33]
	v_mfma_f32_16x16x32_bf16 v[26:29], v[206:209], v[166:169], v[26:29]
	v_mfma_f32_16x16x32_bf16 v[22:25], v[198:201], v[174:177], v[22:25]
	v_mfma_f32_16x16x32_bf16 v[18:21], v[206:209], v[174:177], v[18:21]
	v_mfma_f32_16x16x32_bf16 v[14:17], v[198:201], v[182:185], v[14:17]
	v_mfma_f32_16x16x32_bf16 v[10:13], v[206:209], v[182:185], v[10:13]
	v_mfma_f32_16x16x32_bf16 v[6:9], v[198:201], v[190:193], v[6:9]
	v_mfma_f32_16x16x32_bf16 v[2:5], v[206:209], v[190:193], v[2:5]
	s_mov_b32 s99, 0
.Lz2e_p1:
	s_setprio 0
	s_add_i32 s0, 0, 0x18000
	v_add_u32_e32 v158, s0, v154
	s_barrier
	s_add_i32 s1, 0, 0x1c000
	v_add_u32_e32 v206, s1, v154
	ds_read_b128 v[130:133], v158
	ds_read_b128 v[134:137], v158 offset:1024
	ds_read_b128 v[148:151], v158 offset:2048
	ds_read_b128 v[158:161], v158 offset:3072
	ds_read_b128 v[194:197], v206
	ds_read_b128 v[198:201], v206 offset:1024
	ds_read_b128 v[202:205], v206 offset:2048
	ds_read_b128 v[206:209], v206 offset:3072
	s_mov_b32 m0, s25
	v_lshl_add_u64 v[252:253], v[212:213], 0, s[16:17]
	ds_read_b128 v[162:165], v156 offset:32768
	ds_read_b128 v[166:169], v156 offset:33792
	ds_read_b128 v[170:173], v156 offset:34816
	ds_read_b128 v[174:177], v156 offset:35840
	ds_read_b128 v[178:181], v156 offset:36864
	ds_read_b128 v[182:185], v156 offset:37888
	ds_read_b128 v[186:189], v156 offset:38912
	ds_read_b128 v[190:193], v156 offset:39936
	global_load_lds_dwordx4 v[252:253], off
	v_lshl_add_u64 v[252:253], v[212:213], 0, s[18:19]
	s_mov_b32 m0, s26
	s_nop 0
	global_load_lds_dwordx4 v[252:253], off
	s_waitcnt vmcnt(8)
	s_waitcnt lgkmcnt(0)
	s_barrier
	s_setprio 1
	v_mfma_f32_16x16x32_bf16 v[126:129], v[130:133], v[162:165], v[126:129]
	v_mfma_f32_16x16x32_bf16 v[122:125], v[148:151], v[162:165], v[122:125]
	v_mfma_f32_16x16x32_bf16 v[118:121], v[130:133], v[170:173], v[118:121]
	v_mfma_f32_16x16x32_bf16 v[114:117], v[148:151], v[170:173], v[114:117]
	v_mfma_f32_16x16x32_bf16 v[110:113], v[130:133], v[178:181], v[110:113]
	v_mfma_f32_16x16x32_bf16 v[106:109], v[148:151], v[178:181], v[106:109]
	v_mfma_f32_16x16x32_bf16 v[102:105], v[130:133], v[186:189], v[102:105]
	v_mfma_f32_16x16x32_bf16 v[98:101], v[148:151], v[186:189], v[98:101]
	v_mfma_f32_16x16x32_bf16 v[126:129], v[134:137], v[166:169], v[126:129]
	v_mfma_f32_16x16x32_bf16 v[122:125], v[158:161], v[166:169], v[122:125]
	v_mfma_f32_16x16x32_bf16 v[118:121], v[134:137], v[174:177], v[118:121]
	v_mfma_f32_16x16x32_bf16 v[114:117], v[158:161], v[174:177], v[114:117]
	v_mfma_f32_16x16x32_bf16 v[110:113], v[134:137], v[182:185], v[110:113]
	v_mfma_f32_16x16x32_bf16 v[106:109], v[158:161], v[182:185], v[106:109]
	v_mfma_f32_16x16x32_bf16 v[102:105], v[134:137], v[190:193], v[102:105]
	v_mfma_f32_16x16x32_bf16 v[98:101], v[158:161], v[190:193], v[98:101]
	v_mfma_f32_16x16x32_bf16 v[62:65], v[194:197], v[162:165], v[62:65]
	v_mfma_f32_16x16x32_bf16 v[58:61], v[202:205], v[162:165], v[58:61]
	v_mfma_f32_16x16x32_bf16 v[54:57], v[194:197], v[170:173], v[54:57]
	v_mfma_f32_16x16x32_bf16 v[50:53], v[202:205], v[170:173], v[50:53]
	v_mfma_f32_16x16x32_bf16 v[46:49], v[194:197], v[178:181], v[46:49]
	v_mfma_f32_16x16x32_bf16 v[42:45], v[202:205], v[178:181], v[42:45]
	v_mfma_f32_16x16x32_bf16 v[38:41], v[194:197], v[186:189], v[38:41]
	v_mfma_f32_16x16x32_bf16 v[34:37], v[202:205], v[186:189], v[34:37]
	v_mfma_f32_16x16x32_bf16 v[62:65], v[198:201], v[166:169], v[62:65]
	v_mfma_f32_16x16x32_bf16 v[58:61], v[206:209], v[166:169], v[58:61]
	v_mfma_f32_16x16x32_bf16 v[54:57], v[198:201], v[174:177], v[54:57]
	v_mfma_f32_16x16x32_bf16 v[50:53], v[206:209], v[174:177], v[50:53]
	v_mfma_f32_16x16x32_bf16 v[46:49], v[198:201], v[182:185], v[46:49]
	v_mfma_f32_16x16x32_bf16 v[42:45], v[206:209], v[182:185], v[42:45]
	v_mfma_f32_16x16x32_bf16 v[38:41], v[198:201], v[190:193], v[38:41]
	v_mfma_f32_16x16x32_bf16 v[34:37], v[206:209], v[190:193], v[34:37]
	s_setprio 0
	s_barrier
	ds_read_b128 v[162:165], v156 offset:49152
	ds_read_b128 v[166:169], v156 offset:50176
	ds_read_b128 v[170:173], v156 offset:51200
	ds_read_b128 v[174:177], v156 offset:52224
	ds_read_b128 v[178:181], v156 offset:53248
	ds_read_b128 v[182:185], v156 offset:54272
	ds_read_b128 v[186:189], v156 offset:55296
	ds_read_b128 v[190:193], v156 offset:56320
	s_add_i32 s0, s0, s5
	v_lshl_add_u64 v[214:215], v[210:211], 0, s[38:39]
	s_mov_b32 m0, s0
	s_nop 0
	global_load_lds_dwordx4 v[214:215], off
	v_lshl_add_u64 v[214:215], v[210:211], 0, s[42:43]
	s_add_i32 m0, s0, 0x2000
	s_nop 0
	global_load_lds_dwordx4 v[214:215], off
	s_add_i32 s0, s1, s5
	v_lshl_add_u64 v[250:251], v[210:211], 0, s[44:45]
	s_mov_b32 m0, s0
	s_nop 0
	global_load_lds_dwordx4 v[250:251], off
	v_lshl_add_u64 v[250:251], v[210:211], 0, s[46:47]
	s_add_i32 m0, s0, 0x2000
	s_nop 0
	global_load_lds_dwordx4 v[250:251], off
	s_mov_b32 m0, s37
	v_lshl_add_u64 v[214:215], v[212:213], 0, s[38:39]
	global_load_lds_dwordx4 v[214:215], off
	v_lshl_add_u64 v[212:213], v[212:213], 0, s[42:43]
	s_mov_b32 m0, s40
	s_nop 0
	global_load_lds_dwordx4 v[212:213], off
	s_waitcnt vmcnt(8)
	s_waitcnt lgkmcnt(0)
	s_barrier
	s_setprio 1
	v_mfma_f32_16x16x32_bf16 v[94:97], v[130:133], v[162:165], v[94:97]
	v_mfma_f32_16x16x32_bf16 v[90:93], v[148:151], v[162:165], v[90:93]
	v_mfma_f32_16x16x32_bf16 v[86:89], v[130:133], v[170:173], v[86:89]
	v_mfma_f32_16x16x32_bf16 v[82:85], v[148:151], v[170:173], v[82:85]
	v_mfma_f32_16x16x32_bf16 v[78:81], v[130:133], v[178:181], v[78:81]
	v_mfma_f32_16x16x32_bf16 v[74:77], v[148:151], v[178:181], v[74:77]
	v_mfma_f32_16x16x32_bf16 v[70:73], v[130:133], v[186:189], v[70:73]
	v_mfma_f32_16x16x32_bf16 v[66:69], v[148:151], v[186:189], v[66:69]
	v_mfma_f32_16x16x32_bf16 v[94:97], v[134:137], v[166:169], v[94:97]
	v_mfma_f32_16x16x32_bf16 v[90:93], v[158:161], v[166:169], v[90:93]
	v_mfma_f32_16x16x32_bf16 v[86:89], v[134:137], v[174:177], v[86:89]
	v_mfma_f32_16x16x32_bf16 v[82:85], v[158:161], v[174:177], v[82:85]
	v_mfma_f32_16x16x32_bf16 v[78:81], v[134:137], v[182:185], v[78:81]
	v_mfma_f32_16x16x32_bf16 v[74:77], v[158:161], v[182:185], v[74:77]
	v_mfma_f32_16x16x32_bf16 v[70:73], v[134:137], v[190:193], v[70:73]
	v_mfma_f32_16x16x32_bf16 v[66:69], v[158:161], v[190:193], v[66:69]
	v_mfma_f32_16x16x32_bf16 v[30:33], v[194:197], v[162:165], v[30:33]
	v_mfma_f32_16x16x32_bf16 v[26:29], v[202:205], v[162:165], v[26:29]
	v_mfma_f32_16x16x32_bf16 v[22:25], v[194:197], v[170:173], v[22:25]
	v_mfma_f32_16x16x32_bf16 v[18:21], v[202:205], v[170:173], v[18:21]
	v_mfma_f32_16x16x32_bf16 v[14:17], v[194:197], v[178:181], v[14:17]
	v_mfma_f32_16x16x32_bf16 v[10:13], v[202:205], v[178:181], v[10:13]
	v_mfma_f32_16x16x32_bf16 v[6:9], v[194:197], v[186:189], v[6:9]
	v_mfma_f32_16x16x32_bf16 v[2:5], v[202:205], v[186:189], v[2:5]
	v_mfma_f32_16x16x32_bf16 v[30:33], v[198:201], v[166:169], v[30:33]
	v_mfma_f32_16x16x32_bf16 v[26:29], v[206:209], v[166:169], v[26:29]
	v_mfma_f32_16x16x32_bf16 v[22:25], v[198:201], v[174:177], v[22:25]
	v_mfma_f32_16x16x32_bf16 v[18:21], v[206:209], v[174:177], v[18:21]
	v_mfma_f32_16x16x32_bf16 v[14:17], v[198:201], v[182:185], v[14:17]
	v_mfma_f32_16x16x32_bf16 v[10:13], v[206:209], v[182:185], v[10:13]
	v_mfma_f32_16x16x32_bf16 v[6:9], v[198:201], v[190:193], v[6:9]
	v_mfma_f32_16x16x32_bf16 v[2:5], v[206:209], v[190:193], v[2:5]
	s_setprio 0
	s_add_i32 s68, s68, 2
	s_add_u32 s66, s66, 0x100
	s_addc_u32 s67, s67, 0
	s_add_u32 s64, s64, 0x100
	s_addc_u32 s65, s65, 0
	s_cmp_gt_u32 s68, 13
	s_barrier
	s_cbranch_scc0 .LBB0_190
	s_mov_b32 s98, 1
	s_and_b64 vcc, exec, s[48:49]
	s_cbranch_vccz .LBB0_193
	s_barrier

.LBB0_1048:
	s_add_u32 s38, s68, 0x100
	s_addc_u32 s68, s69, 0
	s_add_u32 s66, s66, 0x40080
	v_mov_b32_e32 v2, 0
	s_addc_u32 s67, s67, 0
	s_mov_b32 s69, -2
	s_mov_b32 s99, 1

.Lz1e_p7:
	s_setprio 0
	s_barrier
	ds_read_b128 v[162:165], v156 offset:16384
	ds_read_b128 v[166:169], v156 offset:17408
	ds_read_b128 v[170:173], v156 offset:18432
	ds_read_b128 v[174:177], v156 offset:19456
	ds_read_b128 v[178:181], v156 offset:20480
	ds_read_b128 v[182:185], v156 offset:21504
	ds_read_b128 v[186:189], v156 offset:22528
	ds_read_b128 v[190:193], v156 offset:23552
	v_lshl_add_u64 v[212:213], s[0:1], 0, v[140:141]
	v_lshl_add_u64 v[210:211], s[30:31], 0, v[138:139]
	s_add_i32 s30, s78, s7
	s_mov_b32 m0, s30
	s_nop 0
	global_load_lds_dwordx4 v[210:211], off
	v_lshl_add_u64 v[214:215], v[210:211], 0, s[14:15]
	s_add_i32 m0, s30, 0x2000
	s_nop 0
	global_load_lds_dwordx4 v[214:215], off
	s_add_i32 s0, s79, s7
	v_lshl_add_u64 v[250:251], v[210:211], 0, s[18:19]
	s_mov_b32 m0, s0
	s_nop 0
	global_load_lds_dwordx4 v[250:251], off
	v_lshl_add_u64 v[250:251], v[210:211], 0, s[20:21]
	s_add_i32 m0, s0, 0x2000
	s_nop 0
	global_load_lds_dwordx4 v[250:251], off
	s_mov_b32 m0, s9
	s_nop 0
	global_load_lds_dwordx4 v[212:213], off
	v_lshl_add_u64 v[214:215], v[212:213], 0, s[14:15]
	s_mov_b32 m0, s24
	s_nop 0
	global_load_lds_dwordx4 v[214:215], off
	s_cmp_lg_u32 s98, 0
	s_cbranch_scc1 .Lsk2_p7
	s_waitcnt vmcnt(8)
	s_branch .Lsk3_p7

.Lz2e_p7:
	s_setprio 0
	s_add_i32 s0, 0, 0x18000
	v_add_u32_e32 v158, s0, v154
	s_barrier
	s_add_i32 s1, 0, 0x1c000
	v_add_u32_e32 v206, s1, v154
	ds_read_b128 v[130:133], v158
	ds_read_b128 v[134:137], v158 offset:1024
	ds_read_b128 v[148:151], v158 offset:2048
	ds_read_b128 v[158:161], v158 offset:3072
	ds_read_b128 v[194:197], v206
	ds_read_b128 v[198:201], v206 offset:1024
	ds_read_b128 v[202:205], v206 offset:2048
	ds_read_b128 v[206:209], v206 offset:3072
	s_mov_b32 m0, s25
	v_lshl_add_u64 v[252:253], v[212:213], 0, s[18:19]
	ds_read_b128 v[162:165], v156 offset:32768
	ds_read_b128 v[166:169], v156 offset:33792
	ds_read_b128 v[170:173], v156 offset:34816
	ds_read_b128 v[174:177], v156 offset:35840
	ds_read_b128 v[178:181], v156 offset:36864
	ds_read_b128 v[182:185], v156 offset:37888
	ds_read_b128 v[186:189], v156 offset:38912
	ds_read_b128 v[190:193], v156 offset:39936
	global_load_lds_dwordx4 v[252:253], off
	v_lshl_add_u64 v[252:253], v[212:213], 0, s[20:21]
	s_mov_b32 m0, s26
	s_nop 0
	global_load_lds_dwordx4 v[252:253], off
	s_waitcnt vmcnt(8)
	s_waitcnt lgkmcnt(0)
	s_barrier
	s_setprio 1
	v_mfma_f32_16x16x32_bf16 v[126:129], v[130:133], v[162:165], v[126:129]
	v_mfma_f32_16x16x32_bf16 v[122:125], v[148:151], v[162:165], v[122:125]
	v_mfma_f32_16x16x32_bf16 v[118:121], v[130:133], v[170:173], v[118:121]
	v_mfma_f32_16x16x32_bf16 v[114:117], v[148:151], v[170:173], v[114:117]
	v_mfma_f32_16x16x32_bf16 v[110:113], v[130:133], v[178:181], v[110:113]
	v_mfma_f32_16x16x32_bf16 v[106:109], v[148:151], v[178:181], v[106:109]
	v_mfma_f32_16x16x32_bf16 v[102:105], v[130:133], v[186:189], v[102:105]
	v_mfma_f32_16x16x32_bf16 v[98:101], v[148:151], v[186:189], v[98:101]
	v_mfma_f32_16x16x32_bf16 v[126:129], v[134:137], v[166:169], v[126:129]
	v_mfma_f32_16x16x32_bf16 v[122:125], v[158:161], v[166:169], v[122:125]
	v_mfma_f32_16x16x32_bf16 v[118:121], v[134:137], v[174:177], v[118:121]
	v_mfma_f32_16x16x32_bf16 v[114:117], v[158:161], v[174:177], v[114:117]
	v_mfma_f32_16x16x32_bf16 v[110:113], v[134:137], v[182:185], v[110:113]
	v_mfma_f32_16x16x32_bf16 v[106:109], v[158:161], v[182:185], v[106:109]
	v_mfma_f32_16x16x32_bf16 v[102:105], v[134:137], v[190:193], v[102:105]
	v_mfma_f32_16x16x32_bf16 v[98:101], v[158:161], v[190:193], v[98:101]
	v_mfma_f32_16x16x32_bf16 v[62:65], v[194:197], v[162:165], v[62:65]
	v_mfma_f32_16x16x32_bf16 v[58:61], v[202:205], v[162:165], v[58:61]
	v_mfma_f32_16x16x32_bf16 v[54:57], v[194:197], v[170:173], v[54:57]
	v_mfma_f32_16x16x32_bf16 v[50:53], v[202:205], v[170:173], v[50:53]
	v_mfma_f32_16x16x32_bf16 v[46:49], v[194:197], v[178:181], v[46:49]
	v_mfma_f32_16x16x32_bf16 v[42:45], v[202:205], v[178:181], v[42:45]
	v_mfma_f32_16x16x32_bf16 v[38:41], v[194:197], v[186:189], v[38:41]
	v_mfma_f32_16x16x32_bf16 v[34:37], v[202:205], v[186:189], v[34:37]
	v_mfma_f32_16x16x32_bf16 v[62:65], v[198:201], v[166:169], v[62:65]
	v_mfma_f32_16x16x32_bf16 v[58:61], v[206:209], v[166:169], v[58:61]
	v_mfma_f32_16x16x32_bf16 v[54:57], v[198:201], v[174:177], v[54:57]
	v_mfma_f32_16x16x32_bf16 v[50:53], v[206:209], v[174:177], v[50:53]
	v_mfma_f32_16x16x32_bf16 v[46:49], v[198:201], v[182:185], v[46:49]
	v_mfma_f32_16x16x32_bf16 v[42:45], v[206:209], v[182:185], v[42:45]
	v_mfma_f32_16x16x32_bf16 v[38:41], v[198:201], v[190:193], v[38:41]
	v_mfma_f32_16x16x32_bf16 v[34:37], v[206:209], v[190:193], v[34:37]
	s_setprio 0
	s_barrier
	ds_read_b128 v[162:165], v156 offset:49152
	ds_read_b128 v[166:169], v156 offset:50176
	ds_read_b128 v[170:173], v156 offset:51200
	ds_read_b128 v[174:177], v156 offset:52224
	ds_read_b128 v[178:181], v156 offset:53248
	ds_read_b128 v[182:185], v156 offset:54272
	ds_read_b128 v[186:189], v156 offset:55296
	ds_read_b128 v[190:193], v156 offset:56320
	s_add_i32 s0, s0, s7
	v_lshl_add_u64 v[214:215], v[210:211], 0, s[42:43]
	s_mov_b32 m0, s0
	s_nop 0
	global_load_lds_dwordx4 v[214:215], off
	v_lshl_add_u64 v[214:215], v[210:211], 0, s[44:45]
	s_add_i32 m0, s0, 0x2000
	s_nop 0
	global_load_lds_dwordx4 v[214:215], off
	s_add_i32 s0, s1, s7
	v_lshl_add_u64 v[250:251], v[210:211], 0, s[46:47]
	s_mov_b32 m0, s0
	s_nop 0
	global_load_lds_dwordx4 v[250:251], off
	v_lshl_add_u64 v[250:251], v[210:211], 0, s[48:49]
	s_add_i32 m0, s0, 0x2000
	s_nop 0
	global_load_lds_dwordx4 v[250:251], off
	s_mov_b32 m0, s72
	v_lshl_add_u64 v[214:215], v[212:213], 0, s[42:43]
	global_load_lds_dwordx4 v[214:215], off
	v_lshl_add_u64 v[212:213], v[212:213], 0, s[44:45]
	s_mov_b32 m0, s73
	s_nop 0
	global_load_lds_dwordx4 v[212:213], off
	s_waitcnt vmcnt(8)
	s_waitcnt lgkmcnt(0)
	s_barrier
	s_setprio 1
	v_mfma_f32_16x16x32_bf16 v[94:97], v[130:133], v[162:165], v[94:97]
	v_mfma_f32_16x16x32_bf16 v[90:93], v[148:151], v[162:165], v[90:93]
	v_mfma_f32_16x16x32_bf16 v[86:89], v[130:133], v[170:173], v[86:89]
	v_mfma_f32_16x16x32_bf16 v[82:85], v[148:151], v[170:173], v[82:85]
	v_mfma_f32_16x16x32_bf16 v[78:81], v[130:133], v[178:181], v[78:81]
	v_mfma_f32_16x16x32_bf16 v[74:77], v[148:151], v[178:181], v[74:77]
	v_mfma_f32_16x16x32_bf16 v[70:73], v[130:133], v[186:189], v[70:73]
	v_mfma_f32_16x16x32_bf16 v[66:69], v[148:151], v[186:189], v[66:69]
	v_mfma_f32_16x16x32_bf16 v[94:97], v[134:137], v[166:169], v[94:97]
	v_mfma_f32_16x16x32_bf16 v[90:93], v[158:161], v[166:169], v[90:93]
	v_mfma_f32_16x16x32_bf16 v[86:89], v[134:137], v[174:177], v[86:89]
	v_mfma_f32_16x16x32_bf16 v[82:85], v[158:161], v[174:177], v[82:85]
	v_mfma_f32_16x16x32_bf16 v[78:81], v[134:137], v[182:185], v[78:81]
	v_mfma_f32_16x16x32_bf16 v[74:77], v[158:161], v[182:185], v[74:77]
	v_mfma_f32_16x16x32_bf16 v[70:73], v[134:137], v[190:193], v[70:73]
	v_mfma_f32_16x16x32_bf16 v[66:69], v[158:161], v[190:193], v[66:69]
	v_mfma_f32_16x16x32_bf16 v[30:33], v[194:197], v[162:165], v[30:33]
	v_mfma_f32_16x16x32_bf16 v[26:29], v[202:205], v[162:165], v[26:29]
	v_mfma_f32_16x16x32_bf16 v[22:25], v[194:197], v[170:173], v[22:25]
	v_mfma_f32_16x16x32_bf16 v[18:21], v[202:205], v[170:173], v[18:21]
	v_mfma_f32_16x16x32_bf16 v[14:17], v[194:197], v[178:181], v[14:17]
	v_mfma_f32_16x16x32_bf16 v[10:13], v[202:205], v[178:181], v[10:13]
	v_mfma_f32_16x16x32_bf16 v[6:9], v[194:197], v[186:189], v[6:9]
	v_mfma_f32_16x16x32_bf16 v[2:5], v[202:205], v[186:189], v[2:5]
	v_mfma_f32_16x16x32_bf16 v[30:33], v[198:201], v[166:169], v[30:33]
	v_mfma_f32_16x16x32_bf16 v[26:29], v[206:209], v[166:169], v[26:29]
	v_mfma_f32_16x16x32_bf16 v[22:25], v[198:201], v[174:177], v[22:25]
	v_mfma_f32_16x16x32_bf16 v[18:21], v[206:209], v[174:177], v[18:21]
	v_mfma_f32_16x16x32_bf16 v[14:17], v[198:201], v[182:185], v[14:17]
	v_mfma_f32_16x16x32_bf16 v[10:13], v[206:209], v[182:185], v[10:13]
	v_mfma_f32_16x16x32_bf16 v[6:9], v[198:201], v[190:193], v[6:9]
	v_mfma_f32_16x16x32_bf16 v[2:5], v[206:209], v[190:193], v[2:5]
	s_setprio 0
	s_add_i32 s69, s69, 2
	s_add_u32 s38, s38, 0x100
	s_addc_u32 s68, s68, 0
	s_add_u32 s66, s66, 0x100
	s_addc_u32 s67, s67, 0
	s_cmp_gt_u32 s69, 13
	s_barrier
	s_cbranch_scc0 .LBB0_1049
	s_mov_b32 s98, 1
	s_and_b64 vcc, exec, s[50:51]
	s_cbranch_vccz .LBB0_1052
	s_barrier

.LBB0_1630:
	s_add_u32 s62, s62, 0x100
	s_addc_u32 s63, s63, 0
	s_add_u32 s60, s60, 0x40080
	v_mov_b32_e32 v2, 0
	s_addc_u32 s61, s61, 0
	s_mov_b32 s79, -2
	s_mov_b32 s99, 1

.Lsk1_p13:
	s_waitcnt lgkmcnt(0)
	s_barrier
	s_setprio 1
	s_cmp_lg_u32 s99, 0
	s_cbranch_scc1 .Lz1_p13
	v_mfma_f32_16x16x32_bf16 v[130:133], v[122:125], v[146:149], v[130:133]
	v_mfma_f32_16x16x32_bf16 v[126:129], v[138:141], v[146:149], v[126:129]
	v_mfma_f32_16x16x32_bf16 v[118:121], v[122:125], v[154:157], v[118:121]
	v_mfma_f32_16x16x32_bf16 v[114:117], v[138:141], v[154:157], v[114:117]
	v_mfma_f32_16x16x32_bf16 v[110:113], v[122:125], v[168:171], v[110:113]
	v_mfma_f32_16x16x32_bf16 v[106:109], v[138:141], v[168:171], v[106:109]
	v_mfma_f32_16x16x32_bf16 v[102:105], v[122:125], v[176:179], v[102:105]
	v_mfma_f32_16x16x32_bf16 v[98:101], v[138:141], v[176:179], v[98:101]
	v_mfma_f32_16x16x32_bf16 v[130:133], v[134:137], v[150:153], v[130:133]
	v_mfma_f32_16x16x32_bf16 v[126:129], v[142:145], v[150:153], v[126:129]
	v_mfma_f32_16x16x32_bf16 v[118:121], v[134:137], v[158:161], v[118:121]
	v_mfma_f32_16x16x32_bf16 v[114:117], v[142:145], v[158:161], v[114:117]
	v_mfma_f32_16x16x32_bf16 v[110:113], v[134:137], v[172:175], v[110:113]
	v_mfma_f32_16x16x32_bf16 v[106:109], v[142:145], v[172:175], v[106:109]
	v_mfma_f32_16x16x32_bf16 v[102:105], v[134:137], v[180:183], v[102:105]
	v_mfma_f32_16x16x32_bf16 v[98:101], v[142:145], v[180:183], v[98:101]
	v_mfma_f32_16x16x32_bf16 v[62:65], v[192:195], v[146:149], v[62:65]
	v_mfma_f32_16x16x32_bf16 v[58:61], v[200:203], v[146:149], v[58:61]
	v_mfma_f32_16x16x32_bf16 v[54:57], v[192:195], v[154:157], v[54:57]
	v_mfma_f32_16x16x32_bf16 v[50:53], v[200:203], v[154:157], v[50:53]
	v_mfma_f32_16x16x32_bf16 v[46:49], v[192:195], v[168:171], v[46:49]
	v_mfma_f32_16x16x32_bf16 v[42:45], v[200:203], v[168:171], v[42:45]
	v_mfma_f32_16x16x32_bf16 v[38:41], v[192:195], v[176:179], v[38:41]
	v_mfma_f32_16x16x32_bf16 v[34:37], v[200:203], v[176:179], v[34:37]
	v_mfma_f32_16x16x32_bf16 v[62:65], v[196:199], v[150:153], v[62:65]
	v_mfma_f32_16x16x32_bf16 v[58:61], v[204:207], v[150:153], v[58:61]
	v_mfma_f32_16x16x32_bf16 v[54:57], v[196:199], v[158:161], v[54:57]
	v_mfma_f32_16x16x32_bf16 v[50:53], v[204:207], v[158:161], v[50:53]
	v_mfma_f32_16x16x32_bf16 v[46:49], v[196:199], v[172:175], v[46:49]
	v_mfma_f32_16x16x32_bf16 v[42:45], v[204:207], v[172:175], v[42:45]
	v_mfma_f32_16x16x32_bf16 v[38:41], v[196:199], v[180:183], v[38:41]
	v_mfma_f32_16x16x32_bf16 v[34:37], v[204:207], v[180:183], v[34:37]
	s_branch .Lz1e_p13
.Lz1_p13:
	v_mfma_f32_16x16x32_bf16 v[130:133], v[122:125], v[146:149], 0
	v_mfma_f32_16x16x32_bf16 v[126:129], v[138:141], v[146:149], 0
	v_mfma_f32_16x16x32_bf16 v[118:121], v[122:125], v[154:157], 0
	v_mfma_f32_16x16x32_bf16 v[114:117], v[138:141], v[154:157], 0
	v_mfma_f32_16x16x32_bf16 v[110:113], v[122:125], v[168:171], 0
	v_mfma_f32_16x16x32_bf16 v[106:109], v[138:141], v[168:171], 0
	v_mfma_f32_16x16x32_bf16 v[102:105], v[122:125], v[176:179], 0
	v_mfma_f32_16x16x32_bf16 v[98:101], v[138:141], v[176:179], 0
	v_mfma_f32_16x16x32_bf16 v[130:133], v[134:137], v[150:153], v[130:133]
	v_mfma_f32_16x16x32_bf16 v[126:129], v[142:145], v[150:153], v[126:129]
	v_mfma_f32_16x16x32_bf16 v[118:121], v[134:137], v[158:161], v[118:121]
	v_mfma_f32_16x16x32_bf16 v[114:117], v[142:145], v[158:161], v[114:117]
	v_mfma_f32_16x16x32_bf16 v[110:113], v[134:137], v[172:175], v[110:113]
	v_mfma_f32_16x16x32_bf16 v[106:109], v[142:145], v[172:175], v[106:109]
	v_mfma_f32_16x16x32_bf16 v[102:105], v[134:137], v[180:183], v[102:105]
	v_mfma_f32_16x16x32_bf16 v[98:101], v[142:145], v[180:183], v[98:101]
	v_mfma_f32_16x16x32_bf16 v[62:65], v[192:195], v[146:149], 0
	v_mfma_f32_16x16x32_bf16 v[58:61], v[200:203], v[146:149], 0
	v_mfma_f32_16x16x32_bf16 v[54:57], v[192:195], v[154:157], 0
	v_mfma_f32_16x16x32_bf16 v[50:53], v[200:203], v[154:157], 0
	v_mfma_f32_16x16x32_bf16 v[46:49], v[192:195], v[168:171], 0
	v_mfma_f32_16x16x32_bf16 v[42:45], v[200:203], v[168:171], 0
	v_mfma_f32_16x16x32_bf16 v[38:41], v[192:195], v[176:179], 0
	v_mfma_f32_16x16x32_bf16 v[34:37], v[200:203], v[176:179], 0
	v_mfma_f32_16x16x32_bf16 v[62:65], v[196:199], v[150:153], v[62:65]
	v_mfma_f32_16x16x32_bf16 v[58:61], v[204:207], v[150:153], v[58:61]
	v_mfma_f32_16x16x32_bf16 v[54:57], v[196:199], v[158:161], v[54:57]
	v_mfma_f32_16x16x32_bf16 v[50:53], v[204:207], v[158:161], v[50:53]
	v_mfma_f32_16x16x32_bf16 v[46:49], v[196:199], v[172:175], v[46:49]
	v_mfma_f32_16x16x32_bf16 v[42:45], v[204:207], v[172:175], v[42:45]
	v_mfma_f32_16x16x32_bf16 v[38:41], v[196:199], v[180:183], v[38:41]
	v_mfma_f32_16x16x32_bf16 v[34:37], v[204:207], v[180:183], v[34:37]
.Lz1e_p13:
	s_setprio 0
	s_barrier
	ds_read_b128 v[146:149], v190 offset:16384
	ds_read_b128 v[150:153], v190 offset:17408
	ds_read_b128 v[154:157], v190 offset:18432
	ds_read_b128 v[158:161], v190 offset:19456
	ds_read_b128 v[168:171], v190 offset:20480
	ds_read_b128 v[172:175], v190 offset:21504
	ds_read_b128 v[176:179], v190 offset:22528
	ds_read_b128 v[180:183], v190 offset:23552
	v_lshl_add_u64 v[208:209], s[0:1], 0, v[164:165]
	v_lshl_add_u64 v[184:185], s[30:31], 0, v[162:163]
	s_add_i32 s30, s72, s5
	s_mov_b32 m0, s30
	s_nop 0
	global_load_lds_dwordx4 v[184:185], off
	v_lshl_add_u64 v[210:211], v[184:185], 0, s[12:13]
	s_add_i32 m0, s30, 0x2000
	s_nop 0
	global_load_lds_dwordx4 v[210:211], off
	s_add_i32 s0, s73, s5
	v_lshl_add_u64 v[250:251], v[184:185], 0, s[14:15]
	s_mov_b32 m0, s0
	s_nop 0
	global_load_lds_dwordx4 v[250:251], off
	v_lshl_add_u64 v[250:251], v[184:185], 0, s[16:17]
	s_add_i32 m0, s0, 0x2000
	s_nop 0
	global_load_lds_dwordx4 v[250:251], off
	s_mov_b32 m0, s6
	s_nop 0
	global_load_lds_dwordx4 v[208:209], off
	v_lshl_add_u64 v[210:211], v[208:209], 0, s[12:13]
	s_mov_b32 m0, s7
	s_nop 0
	global_load_lds_dwordx4 v[210:211], off
	s_cmp_lg_u32 s98, 0
	s_cbranch_scc1 .Lsk2_p13
	s_waitcnt vmcnt(8)
	s_branch .Lsk3_p13

.Lsk3_p13:
	s_waitcnt lgkmcnt(0)
	s_barrier
	s_setprio 1
	s_cmp_lg_u32 s99, 0
	s_cbranch_scc1 .Lz2_p13
	v_mfma_f32_16x16x32_bf16 v[94:97], v[122:125], v[146:149], v[94:97]
	v_mfma_f32_16x16x32_bf16 v[90:93], v[138:141], v[146:149], v[90:93]
	v_mfma_f32_16x16x32_bf16 v[86:89], v[122:125], v[154:157], v[86:89]
	v_mfma_f32_16x16x32_bf16 v[82:85], v[138:141], v[154:157], v[82:85]
	v_mfma_f32_16x16x32_bf16 v[78:81], v[122:125], v[168:171], v[78:81]
	v_mfma_f32_16x16x32_bf16 v[74:77], v[138:141], v[168:171], v[74:77]
	v_mfma_f32_16x16x32_bf16 v[70:73], v[122:125], v[176:179], v[70:73]
	v_mfma_f32_16x16x32_bf16 v[66:69], v[138:141], v[176:179], v[66:69]
	v_mfma_f32_16x16x32_bf16 v[94:97], v[134:137], v[150:153], v[94:97]
	v_mfma_f32_16x16x32_bf16 v[90:93], v[142:145], v[150:153], v[90:93]
	v_mfma_f32_16x16x32_bf16 v[86:89], v[134:137], v[158:161], v[86:89]
	v_mfma_f32_16x16x32_bf16 v[82:85], v[142:145], v[158:161], v[82:85]
	v_mfma_f32_16x16x32_bf16 v[78:81], v[134:137], v[172:175], v[78:81]
	v_mfma_f32_16x16x32_bf16 v[74:77], v[142:145], v[172:175], v[74:77]
	v_mfma_f32_16x16x32_bf16 v[70:73], v[134:137], v[180:183], v[70:73]
	v_mfma_f32_16x16x32_bf16 v[66:69], v[142:145], v[180:183], v[66:69]
	v_mfma_f32_16x16x32_bf16 v[30:33], v[192:195], v[146:149], v[30:33]
	v_mfma_f32_16x16x32_bf16 v[26:29], v[200:203], v[146:149], v[26:29]
	v_mfma_f32_16x16x32_bf16 v[22:25], v[192:195], v[154:157], v[22:25]
	v_mfma_f32_16x16x32_bf16 v[18:21], v[200:203], v[154:157], v[18:21]
	v_mfma_f32_16x16x32_bf16 v[14:17], v[192:195], v[168:171], v[14:17]
	v_mfma_f32_16x16x32_bf16 v[10:13], v[200:203], v[168:171], v[10:13]
	v_mfma_f32_16x16x32_bf16 v[6:9], v[192:195], v[176:179], v[6:9]
	v_mfma_f32_16x16x32_bf16 v[2:5], v[200:203], v[176:179], v[2:5]
	v_mfma_f32_16x16x32_bf16 v[30:33], v[196:199], v[150:153], v[30:33]
	v_mfma_f32_16x16x32_bf16 v[26:29], v[204:207], v[150:153], v[26:29]
	v_mfma_f32_16x16x32_bf16 v[22:25], v[196:199], v[158:161], v[22:25]
	v_mfma_f32_16x16x32_bf16 v[18:21], v[204:207], v[158:161], v[18:21]
	v_mfma_f32_16x16x32_bf16 v[14:17], v[196:199], v[172:175], v[14:17]
	v_mfma_f32_16x16x32_bf16 v[10:13], v[204:207], v[172:175], v[10:13]
	v_mfma_f32_16x16x32_bf16 v[6:9], v[196:199], v[180:183], v[6:9]
	v_mfma_f32_16x16x32_bf16 v[2:5], v[204:207], v[180:183], v[2:5]
	s_branch .Lz2e_p13
.Lz2_p13:
	v_mfma_f32_16x16x32_bf16 v[94:97], v[122:125], v[146:149], 0
	v_mfma_f32_16x16x32_bf16 v[90:93], v[138:141], v[146:149], 0
	v_mfma_f32_16x16x32_bf16 v[86:89], v[122:125], v[154:157], 0
	v_mfma_f32_16x16x32_bf16 v[82:85], v[138:141], v[154:157], 0
	v_mfma_f32_16x16x32_bf16 v[78:81], v[122:125], v[168:171], 0
	v_mfma_f32_16x16x32_bf16 v[74:77], v[138:141], v[168:171], 0
	v_mfma_f32_16x16x32_bf16 v[70:73], v[122:125], v[176:179], 0
	v_mfma_f32_16x16x32_bf16 v[66:69], v[138:141], v[176:179], 0
	v_mfma_f32_16x16x32_bf16 v[94:97], v[134:137], v[150:153], v[94:97]
	v_mfma_f32_16x16x32_bf16 v[90:93], v[142:145], v[150:153], v[90:93]
	v_mfma_f32_16x16x32_bf16 v[86:89], v[134:137], v[158:161], v[86:89]
	v_mfma_f32_16x16x32_bf16 v[82:85], v[142:145], v[158:161], v[82:85]
	v_mfma_f32_16x16x32_bf16 v[78:81], v[134:137], v[172:175], v[78:81]
	v_mfma_f32_16x16x32_bf16 v[74:77], v[142:145], v[172:175], v[74:77]
	v_mfma_f32_16x16x32_bf16 v[70:73], v[134:137], v[180:183], v[70:73]
	v_mfma_f32_16x16x32_bf16 v[66:69], v[142:145], v[180:183], v[66:69]
	v_mfma_f32_16x16x32_bf16 v[30:33], v[192:195], v[146:149], 0
	v_mfma_f32_16x16x32_bf16 v[26:29], v[200:203], v[146:149], 0
	v_mfma_f32_16x16x32_bf16 v[22:25], v[192:195], v[154:157], 0
	v_mfma_f32_16x16x32_bf16 v[18:21], v[200:203], v[154:157], 0
	v_mfma_f32_16x16x32_bf16 v[14:17], v[192:195], v[168:171], 0
	v_mfma_f32_16x16x32_bf16 v[10:13], v[200:203], v[168:171], 0
	v_mfma_f32_16x16x32_bf16 v[6:9], v[192:195], v[176:179], 0
	v_mfma_f32_16x16x32_bf16 v[2:5], v[200:203], v[176:179], 0
	v_mfma_f32_16x16x32_bf16 v[30:33], v[196:199], v[150:153], v[30:33]
	v_mfma_f32_16x16x32_bf16 v[26:29], v[204:207], v[150:153], v[26:29]
	v_mfma_f32_16x16x32_bf16 v[22:25], v[196:199], v[158:161], v[22:25]
	v_mfma_f32_16x16x32_bf16 v[18:21], v[204:207], v[158:161], v[18:21]
	v_mfma_f32_16x16x32_bf16 v[14:17], v[196:199], v[172:175], v[14:17]
	v_mfma_f32_16x16x32_bf16 v[10:13], v[204:207], v[172:175], v[10:13]
	v_mfma_f32_16x16x32_bf16 v[6:9], v[196:199], v[180:183], v[6:9]
	v_mfma_f32_16x16x32_bf16 v[2:5], v[204:207], v[180:183], v[2:5]
	s_mov_b32 s99, 0
.Lz2e_p13:
	s_setprio 0
	s_add_i32 s0, 0, 0x18000
	v_add_u32_e32 v142, s0, v188
	s_barrier
	s_add_i32 s1, 0, 0x1c000
	v_add_u32_e32 v204, s1, v188
	ds_read_b128 v[122:125], v142
	ds_read_b128 v[134:137], v142 offset:1024
	ds_read_b128 v[138:141], v142 offset:2048
	ds_read_b128 v[142:145], v142 offset:3072
	ds_read_b128 v[192:195], v204
	ds_read_b128 v[196:199], v204 offset:1024
	ds_read_b128 v[200:203], v204 offset:2048
	ds_read_b128 v[204:207], v204 offset:3072
	s_mov_b32 m0, s24
	v_lshl_add_u64 v[252:253], v[208:209], 0, s[14:15]
	ds_read_b128 v[146:149], v190 offset:32768
	ds_read_b128 v[150:153], v190 offset:33792
	ds_read_b128 v[154:157], v190 offset:34816
	ds_read_b128 v[158:161], v190 offset:35840
	ds_read_b128 v[168:171], v190 offset:36864
	ds_read_b128 v[172:175], v190 offset:37888
	ds_read_b128 v[176:179], v190 offset:38912
	ds_read_b128 v[180:183], v190 offset:39936
	global_load_lds_dwordx4 v[252:253], off
	v_lshl_add_u64 v[252:253], v[208:209], 0, s[16:17]
	s_mov_b32 m0, s25
	s_nop 0
	global_load_lds_dwordx4 v[252:253], off
	s_waitcnt vmcnt(8)
	s_waitcnt lgkmcnt(0)
	s_barrier
	s_setprio 1
	v_mfma_f32_16x16x32_bf16 v[130:133], v[122:125], v[146:149], v[130:133]
	v_mfma_f32_16x16x32_bf16 v[126:129], v[138:141], v[146:149], v[126:129]
	v_mfma_f32_16x16x32_bf16 v[118:121], v[122:125], v[154:157], v[118:121]
	v_mfma_f32_16x16x32_bf16 v[114:117], v[138:141], v[154:157], v[114:117]
	v_mfma_f32_16x16x32_bf16 v[110:113], v[122:125], v[168:171], v[110:113]
	v_mfma_f32_16x16x32_bf16 v[106:109], v[138:141], v[168:171], v[106:109]
	v_mfma_f32_16x16x32_bf16 v[102:105], v[122:125], v[176:179], v[102:105]
	v_mfma_f32_16x16x32_bf16 v[98:101], v[138:141], v[176:179], v[98:101]
	v_mfma_f32_16x16x32_bf16 v[130:133], v[134:137], v[150:153], v[130:133]
	v_mfma_f32_16x16x32_bf16 v[126:129], v[142:145], v[150:153], v[126:129]
	v_mfma_f32_16x16x32_bf16 v[118:121], v[134:137], v[158:161], v[118:121]
	v_mfma_f32_16x16x32_bf16 v[114:117], v[142:145], v[158:161], v[114:117]
	v_mfma_f32_16x16x32_bf16 v[110:113], v[134:137], v[172:175], v[110:113]
	v_mfma_f32_16x16x32_bf16 v[106:109], v[142:145], v[172:175], v[106:109]
	v_mfma_f32_16x16x32_bf16 v[102:105], v[134:137], v[180:183], v[102:105]
	v_mfma_f32_16x16x32_bf16 v[98:101], v[142:145], v[180:183], v[98:101]
	v_mfma_f32_16x16x32_bf16 v[62:65], v[192:195], v[146:149], v[62:65]
	v_mfma_f32_16x16x32_bf16 v[58:61], v[200:203], v[146:149], v[58:61]
	v_mfma_f32_16x16x32_bf16 v[54:57], v[192:195], v[154:157], v[54:57]
	v_mfma_f32_16x16x32_bf16 v[50:53], v[200:203], v[154:157], v[50:53]
	v_mfma_f32_16x16x32_bf16 v[46:49], v[192:195], v[168:171], v[46:49]
	v_mfma_f32_16x16x32_bf16 v[42:45], v[200:203], v[168:171], v[42:45]
	v_mfma_f32_16x16x32_bf16 v[38:41], v[192:195], v[176:179], v[38:41]
	v_mfma_f32_16x16x32_bf16 v[34:37], v[200:203], v[176:179], v[34:37]
	v_mfma_f32_16x16x32_bf16 v[62:65], v[196:199], v[150:153], v[62:65]
	v_mfma_f32_16x16x32_bf16 v[58:61], v[204:207], v[150:153], v[58:61]
	v_mfma_f32_16x16x32_bf16 v[54:57], v[196:199], v[158:161], v[54:57]
	v_mfma_f32_16x16x32_bf16 v[50:53], v[204:207], v[158:161], v[50:53]
	v_mfma_f32_16x16x32_bf16 v[46:49], v[196:199], v[172:175], v[46:49]
	v_mfma_f32_16x16x32_bf16 v[42:45], v[204:207], v[172:175], v[42:45]
	v_mfma_f32_16x16x32_bf16 v[38:41], v[196:199], v[180:183], v[38:41]
	v_mfma_f32_16x16x32_bf16 v[34:37], v[204:207], v[180:183], v[34:37]
	s_setprio 0
	s_barrier
	ds_read_b128 v[146:149], v190 offset:49152
	ds_read_b128 v[150:153], v190 offset:50176
	ds_read_b128 v[154:157], v190 offset:51200
	ds_read_b128 v[158:161], v190 offset:52224
	ds_read_b128 v[168:171], v190 offset:53248
	ds_read_b128 v[172:175], v190 offset:54272
	ds_read_b128 v[176:179], v190 offset:55296
	ds_read_b128 v[180:183], v190 offset:56320
	s_add_i32 s0, s0, s5
	v_lshl_add_u64 v[210:211], v[184:185], 0, s[22:23]
	s_mov_b32 m0, s0
	s_nop 0
	global_load_lds_dwordx4 v[210:211], off
	v_lshl_add_u64 v[210:211], v[184:185], 0, s[34:35]
	s_add_i32 m0, s0, 0x2000
	s_nop 0
	global_load_lds_dwordx4 v[210:211], off
	s_add_i32 s0, s1, s5
	v_lshl_add_u64 v[250:251], v[184:185], 0, s[36:37]
	s_mov_b32 m0, s0
	s_nop 0
	global_load_lds_dwordx4 v[250:251], off
	v_lshl_add_u64 v[250:251], v[184:185], 0, s[38:39]
	s_add_i32 m0, s0, 0x2000
	s_nop 0
	global_load_lds_dwordx4 v[250:251], off
	s_mov_b32 m0, s66
	v_lshl_add_u64 v[210:211], v[208:209], 0, s[22:23]
	global_load_lds_dwordx4 v[210:211], off
	v_lshl_add_u64 v[208:209], v[208:209], 0, s[34:35]
	s_mov_b32 m0, s67
	s_nop 0
	global_load_lds_dwordx4 v[208:209], off
	s_waitcnt vmcnt(8)
	s_waitcnt lgkmcnt(0)
	s_barrier
	s_setprio 1
	v_mfma_f32_16x16x32_bf16 v[94:97], v[122:125], v[146:149], v[94:97]
	v_mfma_f32_16x16x32_bf16 v[90:93], v[138:141], v[146:149], v[90:93]
	v_mfma_f32_16x16x32_bf16 v[86:89], v[122:125], v[154:157], v[86:89]
	v_mfma_f32_16x16x32_bf16 v[82:85], v[138:141], v[154:157], v[82:85]
	v_mfma_f32_16x16x32_bf16 v[78:81], v[122:125], v[168:171], v[78:81]
	v_mfma_f32_16x16x32_bf16 v[74:77], v[138:141], v[168:171], v[74:77]
	v_mfma_f32_16x16x32_bf16 v[70:73], v[122:125], v[176:179], v[70:73]
	v_mfma_f32_16x16x32_bf16 v[66:69], v[138:141], v[176:179], v[66:69]
	v_mfma_f32_16x16x32_bf16 v[94:97], v[134:137], v[150:153], v[94:97]
	v_mfma_f32_16x16x32_bf16 v[90:93], v[142:145], v[150:153], v[90:93]
	v_mfma_f32_16x16x32_bf16 v[86:89], v[134:137], v[158:161], v[86:89]
	v_mfma_f32_16x16x32_bf16 v[82:85], v[142:145], v[158:161], v[82:85]
	v_mfma_f32_16x16x32_bf16 v[78:81], v[134:137], v[172:175], v[78:81]
	v_mfma_f32_16x16x32_bf16 v[74:77], v[142:145], v[172:175], v[74:77]
	v_mfma_f32_16x16x32_bf16 v[70:73], v[134:137], v[180:183], v[70:73]
	v_mfma_f32_16x16x32_bf16 v[66:69], v[142:145], v[180:183], v[66:69]
	v_mfma_f32_16x16x32_bf16 v[30:33], v[192:195], v[146:149], v[30:33]
	v_mfma_f32_16x16x32_bf16 v[26:29], v[200:203], v[146:149], v[26:29]
	v_mfma_f32_16x16x32_bf16 v[22:25], v[192:195], v[154:157], v[22:25]
	v_mfma_f32_16x16x32_bf16 v[18:21], v[200:203], v[154:157], v[18:21]
	v_mfma_f32_16x16x32_bf16 v[14:17], v[192:195], v[168:171], v[14:17]
	v_mfma_f32_16x16x32_bf16 v[10:13], v[200:203], v[168:171], v[10:13]
	v_mfma_f32_16x16x32_bf16 v[6:9], v[192:195], v[176:179], v[6:9]
	v_mfma_f32_16x16x32_bf16 v[2:5], v[200:203], v[176:179], v[2:5]
	v_mfma_f32_16x16x32_bf16 v[30:33], v[196:199], v[150:153], v[30:33]
	v_mfma_f32_16x16x32_bf16 v[26:29], v[204:207], v[150:153], v[26:29]
	v_mfma_f32_16x16x32_bf16 v[22:25], v[196:199], v[158:161], v[22:25]
	v_mfma_f32_16x16x32_bf16 v[18:21], v[204:207], v[158:161], v[18:21]
	v_mfma_f32_16x16x32_bf16 v[14:17], v[196:199], v[172:175], v[14:17]
	v_mfma_f32_16x16x32_bf16 v[10:13], v[204:207], v[172:175], v[10:13]
	v_mfma_f32_16x16x32_bf16 v[6:9], v[196:199], v[180:183], v[6:9]
	v_mfma_f32_16x16x32_bf16 v[2:5], v[204:207], v[180:183], v[2:5]
	s_setprio 0
	s_add_i32 s79, s79, 2
	s_add_u32 s62, s62, 0x100
	s_addc_u32 s63, s63, 0
	s_add_u32 s60, s60, 0x100
	s_addc_u32 s61, s61, 0
	s_cmp_gt_u32 s79, 13
	s_barrier
	s_cbranch_scc0 .LBB0_1631
	s_mov_b32 s98, 1
	s_and_b64 vcc, exec, s[40:41]
	s_cbranch_vccz .LBB0_1634
	s_barrier

.LBB0_1705:
	s_add_u32 s62, s62, 0x100
	s_addc_u32 s63, s63, 0
	s_add_u32 s60, s60, 0x40080
	v_mov_b32_e32 v2, 0
	s_addc_u32 s61, s61, 0
	s_mov_b32 s86, -2
	s_mov_b32 s99, 1

.Lsk1_p14:
	s_waitcnt lgkmcnt(0)
	s_barrier
	s_setprio 1
	s_cmp_lg_u32 s99, 0
	s_cbranch_scc1 .Lz1_p14
	v_mfma_f32_16x16x32_bf16 v[126:129], v[130:133], v[146:149], v[126:129]
	v_mfma_f32_16x16x32_bf16 v[122:125], v[138:141], v[146:149], v[122:125]
	v_mfma_f32_16x16x32_bf16 v[118:121], v[130:133], v[154:157], v[118:121]
	v_mfma_f32_16x16x32_bf16 v[114:117], v[138:141], v[154:157], v[114:117]
	v_mfma_f32_16x16x32_bf16 v[110:113], v[130:133], v[162:165], v[110:113]
	v_mfma_f32_16x16x32_bf16 v[106:109], v[138:141], v[162:165], v[106:109]
	v_mfma_f32_16x16x32_bf16 v[102:105], v[130:133], v[170:173], v[102:105]
	v_mfma_f32_16x16x32_bf16 v[98:101], v[138:141], v[170:173], v[98:101]
	v_mfma_f32_16x16x32_bf16 v[126:129], v[134:137], v[150:153], v[126:129]
	v_mfma_f32_16x16x32_bf16 v[122:125], v[142:145], v[150:153], v[122:125]
	v_mfma_f32_16x16x32_bf16 v[118:121], v[134:137], v[158:161], v[118:121]
	v_mfma_f32_16x16x32_bf16 v[114:117], v[142:145], v[158:161], v[114:117]
	v_mfma_f32_16x16x32_bf16 v[110:113], v[134:137], v[166:169], v[110:113]
	v_mfma_f32_16x16x32_bf16 v[106:109], v[142:145], v[166:169], v[106:109]
	v_mfma_f32_16x16x32_bf16 v[102:105], v[134:137], v[174:177], v[102:105]
	v_mfma_f32_16x16x32_bf16 v[98:101], v[142:145], v[174:177], v[98:101]
	v_mfma_f32_16x16x32_bf16 v[62:65], v[178:181], v[146:149], v[62:65]
	v_mfma_f32_16x16x32_bf16 v[58:61], v[186:189], v[146:149], v[58:61]
	v_mfma_f32_16x16x32_bf16 v[54:57], v[178:181], v[154:157], v[54:57]
	v_mfma_f32_16x16x32_bf16 v[50:53], v[186:189], v[154:157], v[50:53]
	v_mfma_f32_16x16x32_bf16 v[46:49], v[178:181], v[162:165], v[46:49]
	v_mfma_f32_16x16x32_bf16 v[42:45], v[186:189], v[162:165], v[42:45]
	v_mfma_f32_16x16x32_bf16 v[38:41], v[178:181], v[170:173], v[38:41]
	v_mfma_f32_16x16x32_bf16 v[34:37], v[186:189], v[170:173], v[34:37]
	v_mfma_f32_16x16x32_bf16 v[62:65], v[182:185], v[150:153], v[62:65]
	v_mfma_f32_16x16x32_bf16 v[58:61], v[190:193], v[150:153], v[58:61]
	v_mfma_f32_16x16x32_bf16 v[54:57], v[182:185], v[158:161], v[54:57]
	v_mfma_f32_16x16x32_bf16 v[50:53], v[190:193], v[158:161], v[50:53]
	v_mfma_f32_16x16x32_bf16 v[46:49], v[182:185], v[166:169], v[46:49]
	v_mfma_f32_16x16x32_bf16 v[42:45], v[190:193], v[166:169], v[42:45]
	v_mfma_f32_16x16x32_bf16 v[38:41], v[182:185], v[174:177], v[38:41]
	v_mfma_f32_16x16x32_bf16 v[34:37], v[190:193], v[174:177], v[34:37]
	s_branch .Lz1e_p14
.Lz1_p14:
	v_mfma_f32_16x16x32_bf16 v[126:129], v[130:133], v[146:149], 0
	v_mfma_f32_16x16x32_bf16 v[122:125], v[138:141], v[146:149], 0
	v_mfma_f32_16x16x32_bf16 v[118:121], v[130:133], v[154:157], 0
	v_mfma_f32_16x16x32_bf16 v[114:117], v[138:141], v[154:157], 0
	v_mfma_f32_16x16x32_bf16 v[110:113], v[130:133], v[162:165], 0
	v_mfma_f32_16x16x32_bf16 v[106:109], v[138:141], v[162:165], 0
	v_mfma_f32_16x16x32_bf16 v[102:105], v[130:133], v[170:173], 0
	v_mfma_f32_16x16x32_bf16 v[98:101], v[138:141], v[170:173], 0
	v_mfma_f32_16x16x32_bf16 v[126:129], v[134:137], v[150:153], v[126:129]
	v_mfma_f32_16x16x32_bf16 v[122:125], v[142:145], v[150:153], v[122:125]
	v_mfma_f32_16x16x32_bf16 v[118:121], v[134:137], v[158:161], v[118:121]
	v_mfma_f32_16x16x32_bf16 v[114:117], v[142:145], v[158:161], v[114:117]
	v_mfma_f32_16x16x32_bf16 v[110:113], v[134:137], v[166:169], v[110:113]
	v_mfma_f32_16x16x32_bf16 v[106:109], v[142:145], v[166:169], v[106:109]
	v_mfma_f32_16x16x32_bf16 v[102:105], v[134:137], v[174:177], v[102:105]
	v_mfma_f32_16x16x32_bf16 v[98:101], v[142:145], v[174:177], v[98:101]
	v_mfma_f32_16x16x32_bf16 v[62:65], v[178:181], v[146:149], 0
	v_mfma_f32_16x16x32_bf16 v[58:61], v[186:189], v[146:149], 0
	v_mfma_f32_16x16x32_bf16 v[54:57], v[178:181], v[154:157], 0
	v_mfma_f32_16x16x32_bf16 v[50:53], v[186:189], v[154:157], 0
	v_mfma_f32_16x16x32_bf16 v[46:49], v[178:181], v[162:165], 0
	v_mfma_f32_16x16x32_bf16 v[42:45], v[186:189], v[162:165], 0
	v_mfma_f32_16x16x32_bf16 v[38:41], v[178:181], v[170:173], 0
	v_mfma_f32_16x16x32_bf16 v[34:37], v[186:189], v[170:173], 0
	v_mfma_f32_16x16x32_bf16 v[62:65], v[182:185], v[150:153], v[62:65]
	v_mfma_f32_16x16x32_bf16 v[58:61], v[190:193], v[150:153], v[58:61]
	v_mfma_f32_16x16x32_bf16 v[54:57], v[182:185], v[158:161], v[54:57]
	v_mfma_f32_16x16x32_bf16 v[50:53], v[190:193], v[158:161], v[50:53]
	v_mfma_f32_16x16x32_bf16 v[46:49], v[182:185], v[166:169], v[46:49]
	v_mfma_f32_16x16x32_bf16 v[42:45], v[190:193], v[166:169], v[42:45]
	v_mfma_f32_16x16x32_bf16 v[38:41], v[182:185], v[174:177], v[38:41]
	v_mfma_f32_16x16x32_bf16 v[34:37], v[190:193], v[174:177], v[34:37]
.Lz1e_p14:
	s_setprio 0
	s_barrier
	ds_read_b128 v[146:149], v214 offset:16384
	ds_read_b128 v[150:153], v214 offset:17408
	ds_read_b128 v[154:157], v214 offset:18432
	ds_read_b128 v[158:161], v214 offset:19456
	ds_read_b128 v[162:165], v214 offset:20480
	ds_read_b128 v[166:169], v214 offset:21504
	ds_read_b128 v[170:173], v214 offset:22528
	ds_read_b128 v[174:177], v214 offset:23552
	v_lshl_add_u64 v[202:203], s[0:1], 0, v[194:195]
	v_lshl_add_u64 v[200:201], s[30:31], 0, v[196:197]
	s_add_i32 s30, s73, s5
	s_mov_b32 m0, s30
	s_nop 0
	global_load_lds_dwordx4 v[200:201], off
	v_lshl_add_u64 v[204:205], v[200:201], 0, s[10:11]
	s_add_i32 m0, s30, 0x2000
	s_nop 0
	global_load_lds_dwordx4 v[204:205], off
	s_add_i32 s0, s74, s5
	v_lshl_add_u64 v[250:251], v[200:201], 0, s[16:17]
	s_mov_b32 m0, s0
	s_nop 0
	global_load_lds_dwordx4 v[250:251], off
	v_lshl_add_u64 v[250:251], v[200:201], 0, s[18:19]
	s_add_i32 m0, s0, 0x2000
	s_nop 0
	global_load_lds_dwordx4 v[250:251], off
	s_mov_b32 m0, s6
	s_nop 0
	global_load_lds_dwordx4 v[202:203], off
	v_lshl_add_u64 v[204:205], v[202:203], 0, s[10:11]
	s_mov_b32 m0, s7
	s_nop 0
	global_load_lds_dwordx4 v[204:205], off
	s_cmp_lg_u32 s98, 0
	s_cbranch_scc1 .Lsk2_p14
	s_waitcnt vmcnt(8)
	s_branch .Lsk3_p14

.Lsk3_p14:
	s_waitcnt lgkmcnt(0)
	s_barrier
	s_setprio 1
	s_cmp_lg_u32 s99, 0
	s_cbranch_scc1 .Lz2_p14
	v_mfma_f32_16x16x32_bf16 v[94:97], v[130:133], v[146:149], v[94:97]
	v_mfma_f32_16x16x32_bf16 v[90:93], v[138:141], v[146:149], v[90:93]
	v_mfma_f32_16x16x32_bf16 v[86:89], v[130:133], v[154:157], v[86:89]
	v_mfma_f32_16x16x32_bf16 v[82:85], v[138:141], v[154:157], v[82:85]
	v_mfma_f32_16x16x32_bf16 v[78:81], v[130:133], v[162:165], v[78:81]
	v_mfma_f32_16x16x32_bf16 v[74:77], v[138:141], v[162:165], v[74:77]
	v_mfma_f32_16x16x32_bf16 v[70:73], v[130:133], v[170:173], v[70:73]
	v_mfma_f32_16x16x32_bf16 v[66:69], v[138:141], v[170:173], v[66:69]
	v_mfma_f32_16x16x32_bf16 v[94:97], v[134:137], v[150:153], v[94:97]
	v_mfma_f32_16x16x32_bf16 v[90:93], v[142:145], v[150:153], v[90:93]
	v_mfma_f32_16x16x32_bf16 v[86:89], v[134:137], v[158:161], v[86:89]
	v_mfma_f32_16x16x32_bf16 v[82:85], v[142:145], v[158:161], v[82:85]
	v_mfma_f32_16x16x32_bf16 v[78:81], v[134:137], v[166:169], v[78:81]
	v_mfma_f32_16x16x32_bf16 v[74:77], v[142:145], v[166:169], v[74:77]
	v_mfma_f32_16x16x32_bf16 v[70:73], v[134:137], v[174:177], v[70:73]
	v_mfma_f32_16x16x32_bf16 v[66:69], v[142:145], v[174:177], v[66:69]
	v_mfma_f32_16x16x32_bf16 v[30:33], v[178:181], v[146:149], v[30:33]
	v_mfma_f32_16x16x32_bf16 v[26:29], v[186:189], v[146:149], v[26:29]
	v_mfma_f32_16x16x32_bf16 v[22:25], v[178:181], v[154:157], v[22:25]
	v_mfma_f32_16x16x32_bf16 v[18:21], v[186:189], v[154:157], v[18:21]
	v_mfma_f32_16x16x32_bf16 v[14:17], v[178:181], v[162:165], v[14:17]
	v_mfma_f32_16x16x32_bf16 v[10:13], v[186:189], v[162:165], v[10:13]
	v_mfma_f32_16x16x32_bf16 v[6:9], v[178:181], v[170:173], v[6:9]
	v_mfma_f32_16x16x32_bf16 v[2:5], v[186:189], v[170:173], v[2:5]
	v_mfma_f32_16x16x32_bf16 v[30:33], v[182:185], v[150:153], v[30:33]
	v_mfma_f32_16x16x32_bf16 v[26:29], v[190:193], v[150:153], v[26:29]
	v_mfma_f32_16x16x32_bf16 v[22:25], v[182:185], v[158:161], v[22:25]
	v_mfma_f32_16x16x32_bf16 v[18:21], v[190:193], v[158:161], v[18:21]
	v_mfma_f32_16x16x32_bf16 v[14:17], v[182:185], v[166:169], v[14:17]
	v_mfma_f32_16x16x32_bf16 v[10:13], v[190:193], v[166:169], v[10:13]
	v_mfma_f32_16x16x32_bf16 v[6:9], v[182:185], v[174:177], v[6:9]
	v_mfma_f32_16x16x32_bf16 v[2:5], v[190:193], v[174:177], v[2:5]
	s_branch .Lz2e_p14
.Lz2_p14:
	v_mfma_f32_16x16x32_bf16 v[94:97], v[130:133], v[146:149], 0
	v_mfma_f32_16x16x32_bf16 v[90:93], v[138:141], v[146:149], 0
	v_mfma_f32_16x16x32_bf16 v[86:89], v[130:133], v[154:157], 0
	v_mfma_f32_16x16x32_bf16 v[82:85], v[138:141], v[154:157], 0
	v_mfma_f32_16x16x32_bf16 v[78:81], v[130:133], v[162:165], 0
	v_mfma_f32_16x16x32_bf16 v[74:77], v[138:141], v[162:165], 0
	v_mfma_f32_16x16x32_bf16 v[70:73], v[130:133], v[170:173], 0
	v_mfma_f32_16x16x32_bf16 v[66:69], v[138:141], v[170:173], 0
	v_mfma_f32_16x16x32_bf16 v[94:97], v[134:137], v[150:153], v[94:97]
	v_mfma_f32_16x16x32_bf16 v[90:93], v[142:145], v[150:153], v[90:93]
	v_mfma_f32_16x16x32_bf16 v[86:89], v[134:137], v[158:161], v[86:89]
	v_mfma_f32_16x16x32_bf16 v[82:85], v[142:145], v[158:161], v[82:85]
	v_mfma_f32_16x16x32_bf16 v[78:81], v[134:137], v[166:169], v[78:81]
	v_mfma_f32_16x16x32_bf16 v[74:77], v[142:145], v[166:169], v[74:77]
	v_mfma_f32_16x16x32_bf16 v[70:73], v[134:137], v[174:177], v[70:73]
	v_mfma_f32_16x16x32_bf16 v[66:69], v[142:145], v[174:177], v[66:69]
	v_mfma_f32_16x16x32_bf16 v[30:33], v[178:181], v[146:149], 0
	v_mfma_f32_16x16x32_bf16 v[26:29], v[186:189], v[146:149], 0
	v_mfma_f32_16x16x32_bf16 v[22:25], v[178:181], v[154:157], 0
	v_mfma_f32_16x16x32_bf16 v[18:21], v[186:189], v[154:157], 0
	v_mfma_f32_16x16x32_bf16 v[14:17], v[178:181], v[162:165], 0
	v_mfma_f32_16x16x32_bf16 v[10:13], v[186:189], v[162:165], 0
	v_mfma_f32_16x16x32_bf16 v[6:9], v[178:181], v[170:173], 0
	v_mfma_f32_16x16x32_bf16 v[2:5], v[186:189], v[170:173], 0
	v_mfma_f32_16x16x32_bf16 v[30:33], v[182:185], v[150:153], v[30:33]
	v_mfma_f32_16x16x32_bf16 v[26:29], v[190:193], v[150:153], v[26:29]
	v_mfma_f32_16x16x32_bf16 v[22:25], v[182:185], v[158:161], v[22:25]
	v_mfma_f32_16x16x32_bf16 v[18:21], v[190:193], v[158:161], v[18:21]
	v_mfma_f32_16x16x32_bf16 v[14:17], v[182:185], v[166:169], v[14:17]
	v_mfma_f32_16x16x32_bf16 v[10:13], v[190:193], v[166:169], v[10:13]
	v_mfma_f32_16x16x32_bf16 v[6:9], v[182:185], v[174:177], v[6:9]
	v_mfma_f32_16x16x32_bf16 v[2:5], v[190:193], v[174:177], v[2:5]
	s_mov_b32 s99, 0
.Lz2e_p14:
	s_setprio 0
	s_add_i32 s0, 0, 0x18000
	v_add_u32_e32 v142, s0, v212
	s_barrier
	s_add_i32 s1, 0, 0x1c000
	v_add_u32_e32 v190, s1, v212
	ds_read_b128 v[130:133], v142
	ds_read_b128 v[134:137], v142 offset:1024
	ds_read_b128 v[138:141], v142 offset:2048
	ds_read_b128 v[142:145], v142 offset:3072
	ds_read_b128 v[178:181], v190
	ds_read_b128 v[182:185], v190 offset:1024
	ds_read_b128 v[186:189], v190 offset:2048
	ds_read_b128 v[190:193], v190 offset:3072
	s_mov_b32 m0, s24
	v_lshl_add_u64 v[252:253], v[202:203], 0, s[16:17]
	ds_read_b128 v[146:149], v214 offset:32768
	ds_read_b128 v[150:153], v214 offset:33792
	ds_read_b128 v[154:157], v214 offset:34816
	ds_read_b128 v[158:161], v214 offset:35840
	ds_read_b128 v[162:165], v214 offset:36864
	ds_read_b128 v[166:169], v214 offset:37888
	ds_read_b128 v[170:173], v214 offset:38912
	ds_read_b128 v[174:177], v214 offset:39936
	global_load_lds_dwordx4 v[252:253], off
	v_lshl_add_u64 v[252:253], v[202:203], 0, s[18:19]
	s_mov_b32 m0, s25
	s_nop 0
	global_load_lds_dwordx4 v[252:253], off
	s_waitcnt vmcnt(8)
	s_waitcnt lgkmcnt(0)
	s_barrier
	s_setprio 1
	v_mfma_f32_16x16x32_bf16 v[126:129], v[130:133], v[146:149], v[126:129]
	v_mfma_f32_16x16x32_bf16 v[122:125], v[138:141], v[146:149], v[122:125]
	v_mfma_f32_16x16x32_bf16 v[118:121], v[130:133], v[154:157], v[118:121]
	v_mfma_f32_16x16x32_bf16 v[114:117], v[138:141], v[154:157], v[114:117]
	v_mfma_f32_16x16x32_bf16 v[110:113], v[130:133], v[162:165], v[110:113]
	v_mfma_f32_16x16x32_bf16 v[106:109], v[138:141], v[162:165], v[106:109]
	v_mfma_f32_16x16x32_bf16 v[102:105], v[130:133], v[170:173], v[102:105]
	v_mfma_f32_16x16x32_bf16 v[98:101], v[138:141], v[170:173], v[98:101]
	v_mfma_f32_16x16x32_bf16 v[126:129], v[134:137], v[150:153], v[126:129]
	v_mfma_f32_16x16x32_bf16 v[122:125], v[142:145], v[150:153], v[122:125]
	v_mfma_f32_16x16x32_bf16 v[118:121], v[134:137], v[158:161], v[118:121]
	v_mfma_f32_16x16x32_bf16 v[114:117], v[142:145], v[158:161], v[114:117]
	v_mfma_f32_16x16x32_bf16 v[110:113], v[134:137], v[166:169], v[110:113]
	v_mfma_f32_16x16x32_bf16 v[106:109], v[142:145], v[166:169], v[106:109]
	v_mfma_f32_16x16x32_bf16 v[102:105], v[134:137], v[174:177], v[102:105]
	v_mfma_f32_16x16x32_bf16 v[98:101], v[142:145], v[174:177], v[98:101]
	v_mfma_f32_16x16x32_bf16 v[62:65], v[178:181], v[146:149], v[62:65]
	v_mfma_f32_16x16x32_bf16 v[58:61], v[186:189], v[146:149], v[58:61]
	v_mfma_f32_16x16x32_bf16 v[54:57], v[178:181], v[154:157], v[54:57]
	v_mfma_f32_16x16x32_bf16 v[50:53], v[186:189], v[154:157], v[50:53]
	v_mfma_f32_16x16x32_bf16 v[46:49], v[178:181], v[162:165], v[46:49]
	v_mfma_f32_16x16x32_bf16 v[42:45], v[186:189], v[162:165], v[42:45]
	v_mfma_f32_16x16x32_bf16 v[38:41], v[178:181], v[170:173], v[38:41]
	v_mfma_f32_16x16x32_bf16 v[34:37], v[186:189], v[170:173], v[34:37]
	v_mfma_f32_16x16x32_bf16 v[62:65], v[182:185], v[150:153], v[62:65]
	v_mfma_f32_16x16x32_bf16 v[58:61], v[190:193], v[150:153], v[58:61]
	v_mfma_f32_16x16x32_bf16 v[54:57], v[182:185], v[158:161], v[54:57]
	v_mfma_f32_16x16x32_bf16 v[50:53], v[190:193], v[158:161], v[50:53]
	v_mfma_f32_16x16x32_bf16 v[46:49], v[182:185], v[166:169], v[46:49]
	v_mfma_f32_16x16x32_bf16 v[42:45], v[190:193], v[166:169], v[42:45]
	v_mfma_f32_16x16x32_bf16 v[38:41], v[182:185], v[174:177], v[38:41]
	v_mfma_f32_16x16x32_bf16 v[34:37], v[190:193], v[174:177], v[34:37]
	s_setprio 0
	s_barrier
	ds_read_b128 v[146:149], v214 offset:49152
	ds_read_b128 v[150:153], v214 offset:50176
	ds_read_b128 v[154:157], v214 offset:51200
	ds_read_b128 v[158:161], v214 offset:52224
	ds_read_b128 v[162:165], v214 offset:53248
	ds_read_b128 v[166:169], v214 offset:54272
	ds_read_b128 v[170:173], v214 offset:55296
	ds_read_b128 v[174:177], v214 offset:56320
	s_add_i32 s0, s0, s5
	v_lshl_add_u64 v[204:205], v[200:201], 0, s[38:39]
	s_mov_b32 m0, s0
	s_nop 0
	global_load_lds_dwordx4 v[204:205], off
	v_lshl_add_u64 v[204:205], v[200:201], 0, s[40:41]
	s_add_i32 m0, s0, 0x2000
	s_nop 0
	global_load_lds_dwordx4 v[204:205], off
	s_add_i32 s0, s1, s5
	v_lshl_add_u64 v[250:251], v[200:201], 0, s[42:43]
	s_mov_b32 m0, s0
	s_nop 0
	global_load_lds_dwordx4 v[250:251], off
	v_lshl_add_u64 v[250:251], v[200:201], 0, s[44:45]
	s_add_i32 m0, s0, 0x2000
	s_nop 0
	global_load_lds_dwordx4 v[250:251], off
	s_mov_b32 m0, s65
	v_lshl_add_u64 v[204:205], v[202:203], 0, s[38:39]
	global_load_lds_dwordx4 v[204:205], off
	v_lshl_add_u64 v[202:203], v[202:203], 0, s[40:41]
	s_mov_b32 m0, s66
	s_nop 0
	global_load_lds_dwordx4 v[202:203], off
	s_waitcnt vmcnt(8)
	s_waitcnt lgkmcnt(0)
	s_barrier
	s_setprio 1
	v_mfma_f32_16x16x32_bf16 v[94:97], v[130:133], v[146:149], v[94:97]
	v_mfma_f32_16x16x32_bf16 v[90:93], v[138:141], v[146:149], v[90:93]
	v_mfma_f32_16x16x32_bf16 v[86:89], v[130:133], v[154:157], v[86:89]
	v_mfma_f32_16x16x32_bf16 v[82:85], v[138:141], v[154:157], v[82:85]
	v_mfma_f32_16x16x32_bf16 v[78:81], v[130:133], v[162:165], v[78:81]
	v_mfma_f32_16x16x32_bf16 v[74:77], v[138:141], v[162:165], v[74:77]
	v_mfma_f32_16x16x32_bf16 v[70:73], v[130:133], v[170:173], v[70:73]
	v_mfma_f32_16x16x32_bf16 v[66:69], v[138:141], v[170:173], v[66:69]
	v_mfma_f32_16x16x32_bf16 v[94:97], v[134:137], v[150:153], v[94:97]
	v_mfma_f32_16x16x32_bf16 v[90:93], v[142:145], v[150:153], v[90:93]
	v_mfma_f32_16x16x32_bf16 v[86:89], v[134:137], v[158:161], v[86:89]
	v_mfma_f32_16x16x32_bf16 v[82:85], v[142:145], v[158:161], v[82:85]
	v_mfma_f32_16x16x32_bf16 v[78:81], v[134:137], v[166:169], v[78:81]
	v_mfma_f32_16x16x32_bf16 v[74:77], v[142:145], v[166:169], v[74:77]
	v_mfma_f32_16x16x32_bf16 v[70:73], v[134:137], v[174:177], v[70:73]
	v_mfma_f32_16x16x32_bf16 v[66:69], v[142:145], v[174:177], v[66:69]
	v_mfma_f32_16x16x32_bf16 v[30:33], v[178:181], v[146:149], v[30:33]
	v_mfma_f32_16x16x32_bf16 v[26:29], v[186:189], v[146:149], v[26:29]
	v_mfma_f32_16x16x32_bf16 v[22:25], v[178:181], v[154:157], v[22:25]
	v_mfma_f32_16x16x32_bf16 v[18:21], v[186:189], v[154:157], v[18:21]
	v_mfma_f32_16x16x32_bf16 v[14:17], v[178:181], v[162:165], v[14:17]
	v_mfma_f32_16x16x32_bf16 v[10:13], v[186:189], v[162:165], v[10:13]
	v_mfma_f32_16x16x32_bf16 v[6:9], v[178:181], v[170:173], v[6:9]
	v_mfma_f32_16x16x32_bf16 v[2:5], v[186:189], v[170:173], v[2:5]
	v_mfma_f32_16x16x32_bf16 v[30:33], v[182:185], v[150:153], v[30:33]
	v_mfma_f32_16x16x32_bf16 v[26:29], v[190:193], v[150:153], v[26:29]
	v_mfma_f32_16x16x32_bf16 v[22:25], v[182:185], v[158:161], v[22:25]
	v_mfma_f32_16x16x32_bf16 v[18:21], v[190:193], v[158:161], v[18:21]
	v_mfma_f32_16x16x32_bf16 v[14:17], v[182:185], v[166:169], v[14:17]
	v_mfma_f32_16x16x32_bf16 v[10:13], v[190:193], v[166:169], v[10:13]
	v_mfma_f32_16x16x32_bf16 v[6:9], v[182:185], v[174:177], v[6:9]
	v_mfma_f32_16x16x32_bf16 v[2:5], v[190:193], v[174:177], v[2:5]
	s_setprio 0
	s_add_i32 s86, s86, 2
	s_add_u32 s62, s62, 0x100
	s_addc_u32 s63, s63, 0
	s_add_u32 s60, s60, 0x100
	s_addc_u32 s61, s61, 0
	s_cmp_gt_u32 s86, 13
	s_barrier
	s_cbranch_scc0 .LBB0_1706
	s_mov_b32 s98, 1
	s_and_b64 vcc, exec, s[46:47]
	s_cbranch_vccz .LBB0_1709
	s_barrier
